# final-layer down-projection epilogue: nt hint on the 32 output stores (output is never re-read)
# baseline (speedup 1.0000x reference)
; __device__ __forceinline__ float bflo(unsigned w) { return __uint_as_float(w << 16); }
; __device__ __forceinline__ float bfhi(unsigned w) { return __uint_as_float(w & 0xffff0000u); }
;     __device__ __forceinline__ void operator()(const f32x4 (&acc)[2][2][4][2], const pg8::Unit& u, int wr, int wc, int fr_, int fq_) const {
;         int fr = fr_, fq = fq_; asm volatile("" : "+v"(fr), "+v"(fq));
; #pragma unroll
;         for (int ai = 0; ai < 2; ++ai)
; #pragma unroll
;             for (int m = 0; m < 4; ++m) { const unsigned row = (unsigned)(u.pm * 256 + 128 * ai + 64 * wr + 16 * m + fr);
; #pragma unroll
;                 for (int bj = 0; bj < 2; ++bj) { const unsigned o = row * 1024u + (unsigned)(u.pn * 256 + 64 * wc + 32 * bj + 8 * fq);
;                     const u32x4 rb = *(const u32x4*)(resb + o); const f32x4 a0 = acc[ai][bj][m][0], a1 = acc[ai][bj][m][1];
;                     f32x4 y0, y1; y0[0] = bflo(rb.x) + a0[0]; y0[1] = bfhi(rb.x) + a0[1]; y0[2] = bflo(rb.y) + a0[2]; y0[3] = bfhi(rb.y) + a0[3];
;                     y1[0] = bflo(rb.z) + a1[0]; y1[1] = bfhi(rb.z) + a1[1]; y1[2] = bflo(rb.w) + a1[2]; y1[3] = bfhi(rb.w) + a1[3];
;                     *(f32x4*)(out + o) = y0; *(f32x4*)(out + o + 4) = y1; }
;                 __builtin_amdgcn_sched_barrier(0); }
;     }
.LBB0_1254:
	v_mov_b32_e32 v80, v139
	v_mov_b32_e32 v143, v140
	s_lshl_b32 s18, s48, 8
	s_add_i32 s18, s18, s40
	s_lshl_b32 s19, s49, 8
	s_or_b32 s19, s19, s43
	v_lshlrev_b32_e32 v143, 3, v143
	v_add_lshl_u32 v80, s18, v80, 10
	v_add3_u32 v80, s19, v143, v80
	v_lshl_add_u64 v[144:145], v[80:81], 1, s[8:9]
	v_mov_b32_e32 v228, v144
	v_mov_b32_e32 v229, v145
	global_load_dwordx4 v[160:163], v[228:229], off offset:0
	global_load_dwordx4 v[172:175], v[228:229], off offset:64
	s_mov_b64 s[98:99], 0x8000
	v_lshl_add_u64 v[228:229], v[228:229], 0, s[98:99]
	global_load_dwordx4 v[176:179], v[228:229], off offset:0
	global_load_dwordx4 v[180:183], v[228:229], off offset:64
	s_mov_b64 s[98:99], 0x8000
	v_lshl_add_u64 v[228:229], v[228:229], 0, s[98:99]
	global_load_dwordx4 v[212:215], v[228:229], off offset:0
	global_load_dwordx4 v[216:219], v[228:229], off offset:64
	s_mov_b64 s[98:99], 0x8000
	v_lshl_add_u64 v[228:229], v[228:229], 0, s[98:99]
	global_load_dwordx4 v[220:223], v[228:229], off offset:0
	global_load_dwordx4 v[224:227], v[228:229], off offset:64
	s_waitcnt vmcnt(7)
	v_mov_b32_e32 v152, v160
	v_mov_b32_e32 v153, v161
	v_mov_b32_e32 v154, v162
	v_mov_b32_e32 v155, v163
	v_lshlrev_b32_e32 v144, 16, v152
	v_and_b32_e32 v145, 0xffff0000, v152
	v_pk_add_f32 v[126:127], v[126:127], v[144:145]
	v_lshlrev_b32_e32 v144, 16, v153
	v_and_b32_e32 v145, 0xffff0000, v153
	v_pk_add_f32 v[128:129], v[128:129], v[144:145]
	v_lshlrev_b32_e32 v144, 16, v154
	v_and_b32_e32 v145, 0xffff0000, v154
	v_pk_add_f32 v[122:123], v[122:123], v[144:145]
	v_lshlrev_b32_e32 v144, 16, v155
	v_and_b32_e32 v145, 0xffff0000, v155
	v_pk_add_f32 v[124:125], v[124:125], v[144:145]
	v_lshl_add_u64 v[144:145], v[80:81], 2, s[56:57]
	global_store_dwordx4 v[144:145], v[126:129], off nt
	global_store_dwordx4 v[144:145], v[122:125], off offset:16 nt
	s_nop 0
	v_add_u32_e32 v126, 32, v80
	v_mov_b32_e32 v127, v81
	v_lshl_add_u64 v[122:123], v[126:127], 1, s[8:9]
	s_mov_b64 s[98:99], 0x28000
	v_lshl_add_u64 v[228:229], v[228:229], 0, s[98:99]
	global_load_dwordx4 v[160:163], v[228:229], off offset:0
	s_waitcnt vmcnt(9)
	v_mov_b32_e32 v122, v172
	v_mov_b32_e32 v123, v173
	v_mov_b32_e32 v124, v174
	v_mov_b32_e32 v125, v175
	v_lshlrev_b32_e32 v128, 16, v122
	v_and_b32_e32 v129, 0xffff0000, v122
	v_lshlrev_b32_e32 v122, 16, v123
	v_and_b32_e32 v123, 0xffff0000, v123
	v_pk_add_f32 v[120:121], v[120:121], v[122:123]
	v_lshlrev_b32_e32 v122, 16, v124
	v_and_b32_e32 v123, 0xffff0000, v124
	v_pk_add_f32 v[114:115], v[114:115], v[122:123]
	v_lshlrev_b32_e32 v122, 16, v125
	v_and_b32_e32 v123, 0xffff0000, v125
	v_pk_add_f32 v[118:119], v[118:119], v[128:129]
	v_pk_add_f32 v[116:117], v[116:117], v[122:123]
	v_lshl_add_u64 v[122:123], v[126:127], 2, s[56:57]
	global_store_dwordx4 v[122:123], v[118:121], off nt
	global_store_dwordx4 v[122:123], v[114:117], off offset:16 nt
	s_nop 0
	v_add_u32_e32 v118, 0x4000, v80
	v_mov_b32_e32 v119, v81
	v_lshl_add_u64 v[114:115], v[118:119], 1, s[8:9]
	global_load_dwordx4 v[172:175], v[228:229], off offset:64
	s_waitcnt vmcnt(11)
	v_mov_b32_e32 v114, v176
	v_mov_b32_e32 v115, v177
	v_mov_b32_e32 v116, v178
	v_mov_b32_e32 v117, v179
	v_lshlrev_b32_e32 v120, 16, v114
	v_and_b32_e32 v121, 0xffff0000, v114
	v_lshlrev_b32_e32 v114, 16, v115
	v_and_b32_e32 v115, 0xffff0000, v115
	v_pk_add_f32 v[112:113], v[112:113], v[114:115]
	v_lshlrev_b32_e32 v114, 16, v116
	v_and_b32_e32 v115, 0xffff0000, v116
	v_pk_add_f32 v[106:107], v[106:107], v[114:115]
	v_lshlrev_b32_e32 v114, 16, v117
	v_and_b32_e32 v115, 0xffff0000, v117
	v_pk_add_f32 v[110:111], v[110:111], v[120:121]
	v_pk_add_f32 v[108:109], v[108:109], v[114:115]
	v_lshl_add_u64 v[114:115], v[118:119], 2, s[56:57]
	global_store_dwordx4 v[114:115], v[110:113], off nt
	global_store_dwordx4 v[114:115], v[106:109], off offset:16 nt
	s_nop 0
	v_add_u32_e32 v110, 0x4020, v80
	v_mov_b32_e32 v111, v81
	v_lshl_add_u64 v[106:107], v[110:111], 1, s[8:9]
	s_mov_b64 s[98:99], 0x8000
	v_lshl_add_u64 v[228:229], v[228:229], 0, s[98:99]
	global_load_dwordx4 v[176:179], v[228:229], off offset:0
	s_waitcnt vmcnt(13)
	v_mov_b32_e32 v106, v180
	v_mov_b32_e32 v107, v181
	v_mov_b32_e32 v108, v182
	v_mov_b32_e32 v109, v183
	v_lshlrev_b32_e32 v112, 16, v106
	v_and_b32_e32 v113, 0xffff0000, v106
	v_lshlrev_b32_e32 v106, 16, v107
	v_and_b32_e32 v107, 0xffff0000, v107
	v_pk_add_f32 v[104:105], v[104:105], v[106:107]
	v_lshlrev_b32_e32 v106, 16, v108
	v_and_b32_e32 v107, 0xffff0000, v108
	v_pk_add_f32 v[98:99], v[98:99], v[106:107]
	v_lshlrev_b32_e32 v106, 16, v109
	v_and_b32_e32 v107, 0xffff0000, v109
	v_pk_add_f32 v[102:103], v[102:103], v[112:113]
	v_pk_add_f32 v[100:101], v[100:101], v[106:107]
	v_lshl_add_u64 v[106:107], v[110:111], 2, s[56:57]
	global_store_dwordx4 v[106:107], v[102:105], off nt
	global_store_dwordx4 v[106:107], v[98:101], off offset:16 nt
	s_nop 0
	v_add_u32_e32 v102, 0x8000, v80
	v_mov_b32_e32 v103, v81
	v_lshl_add_u64 v[98:99], v[102:103], 1, s[8:9]
	global_load_dwordx4 v[180:183], v[228:229], off offset:64
	s_waitcnt vmcnt(15)
	v_mov_b32_e32 v98, v212
	v_mov_b32_e32 v99, v213
	v_mov_b32_e32 v100, v214
	v_mov_b32_e32 v101, v215
	v_lshlrev_b32_e32 v104, 16, v98
	v_and_b32_e32 v105, 0xffff0000, v98
	v_lshlrev_b32_e32 v98, 16, v99
	v_and_b32_e32 v99, 0xffff0000, v99
	v_pk_add_f32 v[96:97], v[96:97], v[98:99]
	v_lshlrev_b32_e32 v98, 16, v100
	v_and_b32_e32 v99, 0xffff0000, v100
	v_pk_add_f32 v[90:91], v[90:91], v[98:99]
	v_lshlrev_b32_e32 v98, 16, v101
	v_and_b32_e32 v99, 0xffff0000, v101
	v_pk_add_f32 v[94:95], v[94:95], v[104:105]
	v_pk_add_f32 v[92:93], v[92:93], v[98:99]
	v_lshl_add_u64 v[98:99], v[102:103], 2, s[56:57]
	global_store_dwordx4 v[98:99], v[94:97], off nt
	global_store_dwordx4 v[98:99], v[90:93], off offset:16 nt
	s_nop 0
	v_add_u32_e32 v94, 0x8020, v80
	v_mov_b32_e32 v95, v81
	v_lshl_add_u64 v[90:91], v[94:95], 1, s[8:9]
	s_mov_b64 s[98:99], 0x8000
	v_lshl_add_u64 v[228:229], v[228:229], 0, s[98:99]
	global_load_dwordx4 v[212:215], v[228:229], off offset:0
	s_waitcnt vmcnt(17)
; __device__ __forceinline__ float bflo(unsigned w) { return __uint_as_float(w << 16); }
; __device__ __forceinline__ float bfhi(unsigned w) { return __uint_as_float(w & 0xffff0000u); }
;     __device__ __forceinline__ void operator()(const f32x4 (&acc)[2][2][4][2], const pg8::Unit& u, int wr, int wc, int fr_, int fq_) const {
;     ...
;             for (int m = 0; m < 4; ++m) { const unsigned row = (unsigned)(u.pm * 256 + 128 * ai + 64 * wr + 16 * m + fr);
; #pragma unroll
;                 for (int bj = 0; bj < 2; ++bj) { const unsigned o = row * 1024u + (unsigned)(u.pn * 256 + 64 * wc + 32 * bj + 8 * fq);
;                     const u32x4 rb = *(const u32x4*)(resb + o); const f32x4 a0 = acc[ai][bj][m][0], a1 = acc[ai][bj][m][1];
;                     f32x4 y0, y1; y0[0] = bflo(rb.x) + a0[0]; y0[1] = bfhi(rb.x) + a0[1]; y0[2] = bflo(rb.y) + a0[2]; y0[3] = bfhi(rb.y) + a0[3];
;                     y1[0] = bflo(rb.z) + a1[0]; y1[1] = bfhi(rb.z) + a1[1]; y1[2] = bflo(rb.w) + a1[2]; y1[3] = bfhi(rb.w) + a1[3];
;                     *(f32x4*)(out + o) = y0; *(f32x4*)(out + o + 4) = y1; }
;                 __builtin_amdgcn_sched_barrier(0); }
	v_mov_b32_e32 v90, v216
	v_mov_b32_e32 v91, v217
	v_mov_b32_e32 v92, v218
	v_mov_b32_e32 v93, v219
	v_lshlrev_b32_e32 v96, 16, v90
	v_and_b32_e32 v97, 0xffff0000, v90
	v_lshlrev_b32_e32 v90, 16, v91
	v_and_b32_e32 v91, 0xffff0000, v91
	v_pk_add_f32 v[88:89], v[88:89], v[90:91]
	v_lshlrev_b32_e32 v90, 16, v92
	v_and_b32_e32 v91, 0xffff0000, v92
	v_pk_add_f32 v[82:83], v[82:83], v[90:91]
	v_lshlrev_b32_e32 v90, 16, v93
	v_and_b32_e32 v91, 0xffff0000, v93
	v_pk_add_f32 v[86:87], v[86:87], v[96:97]
	v_pk_add_f32 v[84:85], v[84:85], v[90:91]
	v_lshl_add_u64 v[90:91], v[94:95], 2, s[56:57]
	global_store_dwordx4 v[90:91], v[86:89], off nt
	global_store_dwordx4 v[90:91], v[82:85], off offset:16 nt
	s_nop 0
	v_add_u32_e32 v86, 0xc000, v80
	v_mov_b32_e32 v87, v81
	v_lshl_add_u64 v[82:83], v[86:87], 1, s[8:9]
	global_load_dwordx4 v[216:219], v[228:229], off offset:64
	s_waitcnt vmcnt(19)
	v_mov_b32_e32 v82, v220
	v_mov_b32_e32 v83, v221
	v_mov_b32_e32 v84, v222
	v_mov_b32_e32 v85, v223
	v_lshlrev_b32_e32 v88, 16, v82
	v_and_b32_e32 v89, 0xffff0000, v82
	v_lshlrev_b32_e32 v82, 16, v83
	v_and_b32_e32 v83, 0xffff0000, v83
	v_pk_add_f32 v[78:79], v[78:79], v[82:83]
	v_lshlrev_b32_e32 v82, 16, v84
	v_and_b32_e32 v83, 0xffff0000, v84
	v_pk_add_f32 v[72:73], v[72:73], v[82:83]
	v_lshlrev_b32_e32 v82, 16, v85
	v_and_b32_e32 v83, 0xffff0000, v85
	v_pk_add_f32 v[76:77], v[76:77], v[88:89]
	v_pk_add_f32 v[74:75], v[74:75], v[82:83]
	v_lshl_add_u64 v[82:83], v[86:87], 2, s[56:57]
	global_store_dwordx4 v[82:83], v[76:79], off nt
	global_store_dwordx4 v[82:83], v[72:75], off offset:16 nt
	s_nop 0
	v_add_u32_e32 v76, 0xc020, v80
	v_mov_b32_e32 v77, v81
	v_lshl_add_u64 v[72:73], v[76:77], 1, s[8:9]
	s_mov_b64 s[98:99], 0x8000
	v_lshl_add_u64 v[228:229], v[228:229], 0, s[98:99]
	global_load_dwordx4 v[220:223], v[228:229], off offset:0
	s_waitcnt vmcnt(21)
	v_mov_b32_e32 v72, v224
	v_mov_b32_e32 v73, v225
	v_mov_b32_e32 v74, v226
	v_mov_b32_e32 v75, v227
	v_lshlrev_b32_e32 v78, 16, v72
	v_and_b32_e32 v79, 0xffff0000, v72
	v_lshlrev_b32_e32 v72, 16, v73
	v_and_b32_e32 v73, 0xffff0000, v73
	v_pk_add_f32 v[70:71], v[70:71], v[72:73]
	v_lshlrev_b32_e32 v72, 16, v74
	v_and_b32_e32 v73, 0xffff0000, v74
	v_pk_add_f32 v[64:65], v[64:65], v[72:73]
	v_lshlrev_b32_e32 v72, 16, v75
	v_and_b32_e32 v73, 0xffff0000, v75
	v_pk_add_f32 v[68:69], v[68:69], v[78:79]
	v_pk_add_f32 v[66:67], v[66:67], v[72:73]
	v_lshl_add_u64 v[72:73], v[76:77], 2, s[56:57]
	global_store_dwordx4 v[72:73], v[68:71], off nt
	global_store_dwordx4 v[72:73], v[64:67], off offset:16 nt
	s_nop 0
	v_add_u32_e32 v68, 0x20000, v80
	v_mov_b32_e32 v69, v81
	v_lshl_add_u64 v[64:65], v[68:69], 1, s[8:9]
	global_load_dwordx4 v[224:227], v[228:229], off offset:64
	s_waitcnt vmcnt(21)
	v_mov_b32_e32 v64, v160
	v_mov_b32_e32 v65, v161
	v_mov_b32_e32 v66, v162
	v_mov_b32_e32 v67, v163
	v_lshlrev_b32_e32 v70, 16, v64
	v_and_b32_e32 v71, 0xffff0000, v64
	v_lshlrev_b32_e32 v64, 16, v65
	v_and_b32_e32 v65, 0xffff0000, v65
	v_pk_add_f32 v[62:63], v[62:63], v[64:65]
	v_lshlrev_b32_e32 v64, 16, v66
	v_and_b32_e32 v65, 0xffff0000, v66
	v_pk_add_f32 v[56:57], v[56:57], v[64:65]
	v_lshlrev_b32_e32 v64, 16, v67
	v_and_b32_e32 v65, 0xffff0000, v67
	v_pk_add_f32 v[60:61], v[60:61], v[70:71]
	v_pk_add_f32 v[58:59], v[58:59], v[64:65]
	v_lshl_add_u64 v[64:65], v[68:69], 2, s[56:57]
	global_store_dwordx4 v[64:65], v[60:63], off nt
	global_store_dwordx4 v[64:65], v[56:59], off offset:16 nt
	s_nop 0
	v_add_u32_e32 v60, 0x20020, v80
	v_mov_b32_e32 v61, v81
	v_lshl_add_u64 v[56:57], v[60:61], 1, s[8:9]
	s_waitcnt vmcnt(20)
	v_mov_b32_e32 v56, v172
	v_mov_b32_e32 v57, v173
	v_mov_b32_e32 v58, v174
	v_mov_b32_e32 v59, v175
	v_lshlrev_b32_e32 v62, 16, v56
	v_and_b32_e32 v63, 0xffff0000, v56
	v_lshlrev_b32_e32 v56, 16, v57
	v_and_b32_e32 v57, 0xffff0000, v57
	v_pk_add_f32 v[54:55], v[54:55], v[56:57]
	v_lshlrev_b32_e32 v56, 16, v58
	v_and_b32_e32 v57, 0xffff0000, v58
	v_pk_add_f32 v[48:49], v[48:49], v[56:57]
	v_lshlrev_b32_e32 v56, 16, v59
	v_and_b32_e32 v57, 0xffff0000, v59
	v_pk_add_f32 v[52:53], v[52:53], v[62:63]
	v_pk_add_f32 v[50:51], v[50:51], v[56:57]
	v_lshl_add_u64 v[56:57], v[60:61], 2, s[56:57]
	global_store_dwordx4 v[56:57], v[52:55], off nt
	global_store_dwordx4 v[56:57], v[48:51], off offset:16 nt
	s_nop 0
	v_add_u32_e32 v52, 0x24000, v80
	v_mov_b32_e32 v53, v81
	v_lshl_add_u64 v[48:49], v[52:53], 1, s[8:9]
	s_waitcnt vmcnt(19)
; __device__ __forceinline__ float bflo(unsigned w) { return __uint_as_float(w << 16); }
; __device__ __forceinline__ float bfhi(unsigned w) { return __uint_as_float(w & 0xffff0000u); }
;     __device__ __forceinline__ void operator()(const f32x4 (&acc)[2][2][4][2], const pg8::Unit& u, int wr, int wc, int fr_, int fq_) const {
;     ...
;             for (int m = 0; m < 4; ++m) { const unsigned row = (unsigned)(u.pm * 256 + 128 * ai + 64 * wr + 16 * m + fr);
; #pragma unroll
;                 for (int bj = 0; bj < 2; ++bj) { const unsigned o = row * 1024u + (unsigned)(u.pn * 256 + 64 * wc + 32 * bj + 8 * fq);
;                     const u32x4 rb = *(const u32x4*)(resb + o); const f32x4 a0 = acc[ai][bj][m][0], a1 = acc[ai][bj][m][1];
;                     f32x4 y0, y1; y0[0] = bflo(rb.x) + a0[0]; y0[1] = bfhi(rb.x) + a0[1]; y0[2] = bflo(rb.y) + a0[2]; y0[3] = bfhi(rb.y) + a0[3];
;                     y1[0] = bflo(rb.z) + a1[0]; y1[1] = bfhi(rb.z) + a1[1]; y1[2] = bflo(rb.w) + a1[2]; y1[3] = bfhi(rb.w) + a1[3];
;                     *(f32x4*)(out + o) = y0; *(f32x4*)(out + o + 4) = y1; }
;                 __builtin_amdgcn_sched_barrier(0); }
;     }
	v_mov_b32_e32 v48, v176
	v_mov_b32_e32 v49, v177
	v_mov_b32_e32 v50, v178
	v_mov_b32_e32 v51, v179
	v_lshlrev_b32_e32 v54, 16, v48
	v_and_b32_e32 v55, 0xffff0000, v48
	v_lshlrev_b32_e32 v48, 16, v49
	v_and_b32_e32 v49, 0xffff0000, v49
	v_pk_add_f32 v[46:47], v[46:47], v[48:49]
	v_lshlrev_b32_e32 v48, 16, v50
	v_and_b32_e32 v49, 0xffff0000, v50
	v_pk_add_f32 v[40:41], v[40:41], v[48:49]
	v_lshlrev_b32_e32 v48, 16, v51
	v_and_b32_e32 v49, 0xffff0000, v51
	v_pk_add_f32 v[44:45], v[44:45], v[54:55]
	v_pk_add_f32 v[42:43], v[42:43], v[48:49]
	v_lshl_add_u64 v[48:49], v[52:53], 2, s[56:57]
	global_store_dwordx4 v[48:49], v[44:47], off nt
	global_store_dwordx4 v[48:49], v[40:43], off offset:16 nt
	s_nop 0
	v_add_u32_e32 v44, 0x24020, v80
	v_mov_b32_e32 v45, v81
	v_lshl_add_u64 v[40:41], v[44:45], 1, s[8:9]
	s_waitcnt vmcnt(18)
	v_mov_b32_e32 v40, v180
	v_mov_b32_e32 v41, v181
	v_mov_b32_e32 v42, v182
	v_mov_b32_e32 v43, v183
	v_lshlrev_b32_e32 v46, 16, v40
	v_and_b32_e32 v47, 0xffff0000, v40
	v_lshlrev_b32_e32 v40, 16, v41
	v_and_b32_e32 v41, 0xffff0000, v41
	v_pk_add_f32 v[38:39], v[38:39], v[40:41]
	v_lshlrev_b32_e32 v40, 16, v42
	v_and_b32_e32 v41, 0xffff0000, v42
	v_pk_add_f32 v[32:33], v[32:33], v[40:41]
	v_lshlrev_b32_e32 v40, 16, v43
	v_and_b32_e32 v41, 0xffff0000, v43
	v_pk_add_f32 v[36:37], v[36:37], v[46:47]
	v_pk_add_f32 v[34:35], v[34:35], v[40:41]
	v_lshl_add_u64 v[40:41], v[44:45], 2, s[56:57]
	global_store_dwordx4 v[40:41], v[36:39], off nt
	global_store_dwordx4 v[40:41], v[32:35], off offset:16 nt
	s_nop 0
	v_add_u32_e32 v36, 0x28000, v80
	v_mov_b32_e32 v37, v81
	v_lshl_add_u64 v[32:33], v[36:37], 1, s[8:9]
	s_waitcnt vmcnt(17)
	v_mov_b32_e32 v32, v212
	v_mov_b32_e32 v33, v213
	v_mov_b32_e32 v34, v214
	v_mov_b32_e32 v35, v215
	v_lshlrev_b32_e32 v38, 16, v32
	v_and_b32_e32 v39, 0xffff0000, v32
	v_lshlrev_b32_e32 v32, 16, v33
	v_and_b32_e32 v33, 0xffff0000, v33
	v_pk_add_f32 v[30:31], v[30:31], v[32:33]
	v_lshlrev_b32_e32 v32, 16, v34
	v_and_b32_e32 v33, 0xffff0000, v34
	v_pk_add_f32 v[24:25], v[24:25], v[32:33]
	v_lshlrev_b32_e32 v32, 16, v35
	v_and_b32_e32 v33, 0xffff0000, v35
	v_pk_add_f32 v[28:29], v[28:29], v[38:39]
	v_pk_add_f32 v[26:27], v[26:27], v[32:33]
	v_lshl_add_u64 v[32:33], v[36:37], 2, s[56:57]
	global_store_dwordx4 v[32:33], v[28:31], off nt
	global_store_dwordx4 v[32:33], v[24:27], off offset:16 nt
	s_nop 0
	v_add_u32_e32 v28, 0x28020, v80
	v_mov_b32_e32 v29, v81
	v_lshl_add_u64 v[24:25], v[28:29], 1, s[8:9]
	s_waitcnt vmcnt(16)
	v_mov_b32_e32 v24, v216
	v_mov_b32_e32 v25, v217
	v_mov_b32_e32 v26, v218
	v_mov_b32_e32 v27, v219
	v_lshlrev_b32_e32 v30, 16, v24
	v_and_b32_e32 v31, 0xffff0000, v24
	v_lshlrev_b32_e32 v24, 16, v25
	v_and_b32_e32 v25, 0xffff0000, v25
	v_pk_add_f32 v[22:23], v[22:23], v[24:25]
	v_lshlrev_b32_e32 v24, 16, v26
	v_and_b32_e32 v25, 0xffff0000, v26
	v_pk_add_f32 v[16:17], v[16:17], v[24:25]
	v_lshlrev_b32_e32 v24, 16, v27
	v_and_b32_e32 v25, 0xffff0000, v27
	v_pk_add_f32 v[20:21], v[20:21], v[30:31]
	v_pk_add_f32 v[18:19], v[18:19], v[24:25]
	v_lshl_add_u64 v[24:25], v[28:29], 2, s[56:57]
	global_store_dwordx4 v[24:25], v[20:23], off nt
	global_store_dwordx4 v[24:25], v[16:19], off offset:16 nt
	s_nop 0
	v_add_u32_e32 v20, 0x2c000, v80
	v_mov_b32_e32 v21, v81
	v_lshl_add_u64 v[16:17], v[20:21], 1, s[8:9]
	v_add_u32_e32 v80, 0x2c020, v80
	s_waitcnt vmcnt(15)
	v_mov_b32_e32 v16, v220
	v_mov_b32_e32 v17, v221
	v_mov_b32_e32 v18, v222
	v_mov_b32_e32 v19, v223
	v_lshlrev_b32_e32 v22, 16, v16
	v_and_b32_e32 v23, 0xffff0000, v16
	v_lshlrev_b32_e32 v16, 16, v17
	v_and_b32_e32 v17, 0xffff0000, v17
	v_pk_add_f32 v[14:15], v[14:15], v[16:17]
	v_lshlrev_b32_e32 v16, 16, v18
	v_and_b32_e32 v17, 0xffff0000, v18
	v_pk_add_f32 v[8:9], v[8:9], v[16:17]
	v_lshlrev_b32_e32 v16, 16, v19
	v_and_b32_e32 v17, 0xffff0000, v19
	v_pk_add_f32 v[12:13], v[12:13], v[22:23]
	v_pk_add_f32 v[10:11], v[10:11], v[16:17]
	v_lshl_add_u64 v[16:17], v[20:21], 2, s[56:57]
	global_store_dwordx4 v[16:17], v[12:15], off nt
	global_store_dwordx4 v[16:17], v[8:11], off offset:16 nt
	s_nop 1
	v_lshl_add_u64 v[8:9], v[80:81], 1, s[8:9]
	s_waitcnt vmcnt(14)
	v_mov_b32_e32 v8, v224
	v_mov_b32_e32 v9, v225
	v_mov_b32_e32 v10, v226
	v_mov_b32_e32 v11, v227
	v_lshlrev_b32_e32 v12, 16, v8
	v_and_b32_e32 v13, 0xffff0000, v8
	v_lshlrev_b32_e32 v8, 16, v9
	v_and_b32_e32 v9, 0xffff0000, v9
	v_pk_add_f32 v[6:7], v[6:7], v[8:9]
	v_lshlrev_b32_e32 v8, 16, v10
	v_and_b32_e32 v9, 0xffff0000, v10
	v_pk_add_f32 v[0:1], v[0:1], v[8:9]
	v_lshlrev_b32_e32 v8, 16, v11
	v_and_b32_e32 v9, 0xffff0000, v11
	v_pk_add_f32 v[4:5], v[4:5], v[12:13]
	v_pk_add_f32 v[2:3], v[2:3], v[8:9]
	v_lshl_add_u64 v[8:9], v[80:81], 2, s[56:57]
	global_store_dwordx4 v[8:9], v[4:7], off nt
	global_store_dwordx4 v[8:9], v[0:3], off offset:16 nt
	s_and_b64 vcc, exec, s[4:5]
	s_mov_b64 s[4:5], -1
	s_cbranch_vccnz .LBB0_1239
	s_andn2_b64 vcc, exec, s[10:11]
	s_cbranch_vccnz .LBB0_1238
	s_barrier
	s_branch .LBB0_1238
